# B2 scan: packed FP32 (v_pk_mul/fma_f32) in scanner chain, 16-step sync
# speedup vs baseline: 1.1066x; 1.0324x over previous
.Lb2_u_loop:
	s_waitcnt vmcnt(0) lgkmcnt(0)
	s_barrier
	s_and_b32 s20, s22, 7
	s_lshl_b32 s20, s20, 3
	s_lshr_b32 s21, s22, 5
	s_add_i32 s20, s20, s21
	s_bfe_u32 s33, s22, 0x20003
	s_mul_i32 s28, s20, 0x300000
	s_add_u32 s28, s28, 0xcf90000
	s_add_u32 s28, s94, s28
	s_addc_u32 s29, s95, 0
	v_readfirstlane_b32 s21, v133
	s_cmpk_lt_u32 s21, 0x100
	s_cbranch_scc0 .Lb2_loader
	v_lshrrev_b32_e32 v112, 4, v133
	v_and_b32_e32 v113, 15, v133
	v_lshlrev_b32_e32 v8, 4, v113
	s_lshl_b32 s21, s33, 4
	s_addk_i32 s21, 0x140
	v_add_u32_e32 v9, s21, v112
	v_lshlrev_b32_e32 v9, 2, v9
	v_lshlrev_b32_e32 v10, 6, v112
	v_lshl_add_u32 v10, v113, 2, v10
	v_add_u32_e32 v10, 0xc000, v10
	v_lshlrev_b32_e32 v11, 8, v112
	v_lshl_add_u32 v11, v113, 4, v11
	s_lshl_b32 s21, s76, 6
	s_add_i32 s21, s21, s20
	s_lshl_b32 s21, s21, 14
	s_lshl_b32 s23, s33, 12
	s_add_i32 s21, s21, s23
	s_add_u32 s21, s21, 0x412c000
	s_add_u32 s40, s92, s21
	s_addc_u32 s41, s93, 0
	v_mov_b32_e32 v0, 0
	v_mov_b32_e32 v1, 0
	v_mov_b32_e32 v2, 0
	v_mov_b32_e32 v3, 0
	s_movk_i32 s34, 0x40
	s_setprio 2
	s_barrier
	ds_read_b128 v[12:15], v8 offset:0
	ds_read_b128 v[16:19], v8 offset:256
	ds_read_b128 v[20:23], v8 offset:512
	ds_read_b128 v[24:27], v8 offset:768
	ds_read_b128 v[28:31], v8 offset:1024
	ds_read_b32 v32, v9 offset:0
	ds_read_b128 v[36:39], v8 offset:1536
	ds_read_b128 v[40:43], v8 offset:1792
	ds_read_b128 v[44:47], v8 offset:2048
	ds_read_b128 v[48:51], v8 offset:2304
	ds_read_b128 v[52:55], v8 offset:2560
	ds_read_b32 v56, v9 offset:1536
	ds_read_b128 v[68:71], v8 offset:3072
	ds_read_b128 v[72:75], v8 offset:3328
	ds_read_b128 v[76:79], v8 offset:3584
	ds_read_b128 v[80:83], v8 offset:3840
	ds_read_b128 v[84:87], v8 offset:4096
	ds_read_b32 v88, v9 offset:3072
	s_waitcnt lgkmcnt(0)
.Lb2_scan_loop:
	s_waitcnt lgkmcnt(12)
	v_pk_mul_f32 v[4:5], v[0:1], v[16:17]
	v_pk_mul_f32 v[6:7], v[0:1], v[28:29]
	v_pk_fma_f32 v[4:5], v[2:3], v[18:19], v[4:5]
	v_pk_fma_f32 v[6:7], v[2:3], v[30:31], v[6:7]
	v_add_f32_e32 v4, v4, v5
	v_add_f32_e32 v6, v6, v7
	v_pk_mul_f32 v[0:1], v[0:1], v[12:13]
	v_add_f32_dpp v4, v4, v4 quad_perm:[1,0,3,2] row_mask:0xf bank_mask:0xf bound_ctrl:1
	v_pk_mul_f32 v[2:3], v[2:3], v[14:15]
	ds_write_b32 v10, v6 offset:0
	v_add_f32_dpp v4, v4, v4 quad_perm:[2,3,0,1] row_mask:0xf bank_mask:0xf bound_ctrl:1
	v_pk_fma_f32 v[0:1], v[32:33], v[24:25], v[0:1] op_sel_hi:[0,1,1]
	v_pk_fma_f32 v[2:3], v[32:33], v[26:27], v[2:3] op_sel_hi:[0,1,1]
	v_add_f32_dpp v4, v4, v4 row_half_mirror row_mask:0xf bank_mask:0xf bound_ctrl:1
	ds_read_b128 v[92:95], v8 offset:4608
	ds_read_b128 v[96:99], v8 offset:4864
	v_add_f32_dpp v4, v4, v4 row_mirror row_mask:0xf bank_mask:0xf bound_ctrl:1
	v_pk_fma_f32 v[0:1], v[4:5], v[20:21], v[0:1] op_sel_hi:[0,1,1] neg_lo:[1,0,0] neg_hi:[1,0,0]
	v_pk_fma_f32 v[2:3], v[4:5], v[22:23], v[2:3] op_sel_hi:[0,1,1] neg_lo:[1,0,0] neg_hi:[1,0,0]
	ds_read_b128 v[100:103], v8 offset:5120
	ds_read_b128 v[104:107], v8 offset:5376
	ds_read_b128 v[108:111], v8 offset:5632
	ds_read_b32 v112, v9 offset:4608
	s_waitcnt lgkmcnt(13)
	v_pk_mul_f32 v[4:5], v[0:1], v[40:41]
	v_pk_mul_f32 v[6:7], v[0:1], v[52:53]
	v_pk_fma_f32 v[4:5], v[2:3], v[42:43], v[4:5]
	v_pk_fma_f32 v[6:7], v[2:3], v[54:55], v[6:7]
	v_add_f32_e32 v4, v4, v5
	v_add_f32_e32 v6, v6, v7
	v_pk_mul_f32 v[0:1], v[0:1], v[36:37]
	v_add_f32_dpp v4, v4, v4 quad_perm:[1,0,3,2] row_mask:0xf bank_mask:0xf bound_ctrl:1
	v_pk_mul_f32 v[2:3], v[2:3], v[38:39]
	ds_write_b32 v10, v6 offset:1024
	v_add_f32_dpp v4, v4, v4 quad_perm:[2,3,0,1] row_mask:0xf bank_mask:0xf bound_ctrl:1
	v_pk_fma_f32 v[0:1], v[56:57], v[48:49], v[0:1] op_sel_hi:[0,1,1]
	v_pk_fma_f32 v[2:3], v[56:57], v[50:51], v[2:3] op_sel_hi:[0,1,1]
	v_add_f32_dpp v4, v4, v4 row_half_mirror row_mask:0xf bank_mask:0xf bound_ctrl:1
	ds_read_b128 v[12:15], v8 offset:6144
	ds_read_b128 v[16:19], v8 offset:6400
	v_add_f32_dpp v4, v4, v4 row_mirror row_mask:0xf bank_mask:0xf bound_ctrl:1
	v_pk_fma_f32 v[0:1], v[4:5], v[44:45], v[0:1] op_sel_hi:[0,1,1] neg_lo:[1,0,0] neg_hi:[1,0,0]
	v_pk_fma_f32 v[2:3], v[4:5], v[46:47], v[2:3] op_sel_hi:[0,1,1] neg_lo:[1,0,0] neg_hi:[1,0,0]
	ds_read_b128 v[20:23], v8 offset:6656
	ds_read_b128 v[24:27], v8 offset:6912
	ds_read_b128 v[28:31], v8 offset:7168
	ds_read_b32 v32, v9 offset:6144
	s_waitcnt lgkmcnt(14)
	v_pk_mul_f32 v[4:5], v[0:1], v[72:73]
	v_pk_mul_f32 v[6:7], v[0:1], v[84:85]
	v_pk_fma_f32 v[4:5], v[2:3], v[74:75], v[4:5]
	v_pk_fma_f32 v[6:7], v[2:3], v[86:87], v[6:7]
	v_add_f32_e32 v4, v4, v5
	v_add_f32_e32 v6, v6, v7
	v_pk_mul_f32 v[0:1], v[0:1], v[68:69]
	v_add_f32_dpp v4, v4, v4 quad_perm:[1,0,3,2] row_mask:0xf bank_mask:0xf bound_ctrl:1
	v_pk_mul_f32 v[2:3], v[2:3], v[70:71]
	ds_write_b32 v10, v6 offset:2048
	v_add_f32_dpp v4, v4, v4 quad_perm:[2,3,0,1] row_mask:0xf bank_mask:0xf bound_ctrl:1
	v_pk_fma_f32 v[0:1], v[88:89], v[80:81], v[0:1] op_sel_hi:[0,1,1]
	v_pk_fma_f32 v[2:3], v[88:89], v[82:83], v[2:3] op_sel_hi:[0,1,1]
	v_add_f32_dpp v4, v4, v4 row_half_mirror row_mask:0xf bank_mask:0xf bound_ctrl:1
	ds_read_b128 v[36:39], v8 offset:7680
	ds_read_b128 v[40:43], v8 offset:7936
	v_add_f32_dpp v4, v4, v4 row_mirror row_mask:0xf bank_mask:0xf bound_ctrl:1
	v_pk_fma_f32 v[0:1], v[4:5], v[76:77], v[0:1] op_sel_hi:[0,1,1] neg_lo:[1,0,0] neg_hi:[1,0,0]
	v_pk_fma_f32 v[2:3], v[4:5], v[78:79], v[2:3] op_sel_hi:[0,1,1] neg_lo:[1,0,0] neg_hi:[1,0,0]
	ds_read_b128 v[44:47], v8 offset:8192
	ds_read_b128 v[48:51], v8 offset:8448
	ds_read_b128 v[52:55], v8 offset:8704
	ds_read_b32 v56, v9 offset:7680
	s_waitcnt lgkmcnt(14)
	v_pk_mul_f32 v[4:5], v[0:1], v[96:97]
	v_pk_mul_f32 v[6:7], v[0:1], v[108:109]
	v_pk_fma_f32 v[4:5], v[2:3], v[98:99], v[4:5]
	v_pk_fma_f32 v[6:7], v[2:3], v[110:111], v[6:7]
	v_add_f32_e32 v4, v4, v5
	v_add_f32_e32 v6, v6, v7
	v_pk_mul_f32 v[0:1], v[0:1], v[92:93]
	v_add_f32_dpp v4, v4, v4 quad_perm:[1,0,3,2] row_mask:0xf bank_mask:0xf bound_ctrl:1
	v_pk_mul_f32 v[2:3], v[2:3], v[94:95]
	ds_write_b32 v10, v6 offset:3072
	v_add_f32_dpp v4, v4, v4 quad_perm:[2,3,0,1] row_mask:0xf bank_mask:0xf bound_ctrl:1
	v_pk_fma_f32 v[0:1], v[112:113], v[104:105], v[0:1] op_sel_hi:[0,1,1]
	v_pk_fma_f32 v[2:3], v[112:113], v[106:107], v[2:3] op_sel_hi:[0,1,1]
	v_add_f32_dpp v4, v4, v4 row_half_mirror row_mask:0xf bank_mask:0xf bound_ctrl:1
	ds_read_b128 v[68:71], v8 offset:9216
	ds_read_b128 v[72:75], v8 offset:9472
	v_add_f32_dpp v4, v4, v4 row_mirror row_mask:0xf bank_mask:0xf bound_ctrl:1
	v_pk_fma_f32 v[0:1], v[4:5], v[100:101], v[0:1] op_sel_hi:[0,1,1] neg_lo:[1,0,0] neg_hi:[1,0,0]
	v_pk_fma_f32 v[2:3], v[4:5], v[102:103], v[2:3] op_sel_hi:[0,1,1] neg_lo:[1,0,0] neg_hi:[1,0,0]
	ds_read_b128 v[76:79], v8 offset:9728
	ds_read_b128 v[80:83], v8 offset:9984
	ds_read_b128 v[84:87], v8 offset:10240
	ds_read_b32 v88, v9 offset:9216
	s_waitcnt lgkmcnt(14)
	v_pk_mul_f32 v[4:5], v[0:1], v[16:17]
	v_pk_mul_f32 v[6:7], v[0:1], v[28:29]
	v_pk_fma_f32 v[4:5], v[2:3], v[18:19], v[4:5]
	v_pk_fma_f32 v[6:7], v[2:3], v[30:31], v[6:7]
	v_add_f32_e32 v4, v4, v5
	v_add_f32_e32 v6, v6, v7
	v_pk_mul_f32 v[0:1], v[0:1], v[12:13]
	v_add_f32_dpp v4, v4, v4 quad_perm:[1,0,3,2] row_mask:0xf bank_mask:0xf bound_ctrl:1
	v_pk_mul_f32 v[2:3], v[2:3], v[14:15]
	ds_write_b32 v10, v6 offset:4096
	v_add_f32_dpp v4, v4, v4 quad_perm:[2,3,0,1] row_mask:0xf bank_mask:0xf bound_ctrl:1
	v_pk_fma_f32 v[0:1], v[32:33], v[24:25], v[0:1] op_sel_hi:[0,1,1]
	v_pk_fma_f32 v[2:3], v[32:33], v[26:27], v[2:3] op_sel_hi:[0,1,1]
	v_add_f32_dpp v4, v4, v4 row_half_mirror row_mask:0xf bank_mask:0xf bound_ctrl:1
	ds_read_b128 v[92:95], v8 offset:10752
	ds_read_b128 v[96:99], v8 offset:11008
	v_add_f32_dpp v4, v4, v4 row_mirror row_mask:0xf bank_mask:0xf bound_ctrl:1
	v_pk_fma_f32 v[0:1], v[4:5], v[20:21], v[0:1] op_sel_hi:[0,1,1] neg_lo:[1,0,0] neg_hi:[1,0,0]
	v_pk_fma_f32 v[2:3], v[4:5], v[22:23], v[2:3] op_sel_hi:[0,1,1] neg_lo:[1,0,0] neg_hi:[1,0,0]
	ds_read_b128 v[100:103], v8 offset:11264
	ds_read_b128 v[104:107], v8 offset:11520
	ds_read_b128 v[108:111], v8 offset:11776
	ds_read_b32 v112, v9 offset:10752
	s_waitcnt lgkmcnt(14)
	v_pk_mul_f32 v[4:5], v[0:1], v[40:41]
	v_pk_mul_f32 v[6:7], v[0:1], v[52:53]
	v_pk_fma_f32 v[4:5], v[2:3], v[42:43], v[4:5]
	v_pk_fma_f32 v[6:7], v[2:3], v[54:55], v[6:7]
	v_add_f32_e32 v4, v4, v5
	v_add_f32_e32 v6, v6, v7
	v_pk_mul_f32 v[0:1], v[0:1], v[36:37]
	v_add_f32_dpp v4, v4, v4 quad_perm:[1,0,3,2] row_mask:0xf bank_mask:0xf bound_ctrl:1
	v_pk_mul_f32 v[2:3], v[2:3], v[38:39]
	ds_write_b32 v10, v6 offset:5120
	v_add_f32_dpp v4, v4, v4 quad_perm:[2,3,0,1] row_mask:0xf bank_mask:0xf bound_ctrl:1
	v_pk_fma_f32 v[0:1], v[56:57], v[48:49], v[0:1] op_sel_hi:[0,1,1]
	v_pk_fma_f32 v[2:3], v[56:57], v[50:51], v[2:3] op_sel_hi:[0,1,1]
	v_add_f32_dpp v4, v4, v4 row_half_mirror row_mask:0xf bank_mask:0xf bound_ctrl:1
	ds_read_b128 v[12:15], v8 offset:12288
	ds_read_b128 v[16:19], v8 offset:12544
	v_add_f32_dpp v4, v4, v4 row_mirror row_mask:0xf bank_mask:0xf bound_ctrl:1
	v_pk_fma_f32 v[0:1], v[4:5], v[44:45], v[0:1] op_sel_hi:[0,1,1] neg_lo:[1,0,0] neg_hi:[1,0,0]
	v_pk_fma_f32 v[2:3], v[4:5], v[46:47], v[2:3] op_sel_hi:[0,1,1] neg_lo:[1,0,0] neg_hi:[1,0,0]
	ds_read_b128 v[20:23], v8 offset:12800
	ds_read_b128 v[24:27], v8 offset:13056
	ds_read_b128 v[28:31], v8 offset:13312
	ds_read_b32 v32, v9 offset:12288
	s_waitcnt lgkmcnt(14)
	v_pk_mul_f32 v[4:5], v[0:1], v[72:73]
	v_pk_mul_f32 v[6:7], v[0:1], v[84:85]
	v_pk_fma_f32 v[4:5], v[2:3], v[74:75], v[4:5]
	v_pk_fma_f32 v[6:7], v[2:3], v[86:87], v[6:7]
	v_add_f32_e32 v4, v4, v5
	v_add_f32_e32 v6, v6, v7
	v_pk_mul_f32 v[0:1], v[0:1], v[68:69]
	v_add_f32_dpp v4, v4, v4 quad_perm:[1,0,3,2] row_mask:0xf bank_mask:0xf bound_ctrl:1
	v_pk_mul_f32 v[2:3], v[2:3], v[70:71]
	ds_write_b32 v10, v6 offset:6144
	v_add_f32_dpp v4, v4, v4 quad_perm:[2,3,0,1] row_mask:0xf bank_mask:0xf bound_ctrl:1
	v_pk_fma_f32 v[0:1], v[88:89], v[80:81], v[0:1] op_sel_hi:[0,1,1]
	v_pk_fma_f32 v[2:3], v[88:89], v[82:83], v[2:3] op_sel_hi:[0,1,1]
	v_add_f32_dpp v4, v4, v4 row_half_mirror row_mask:0xf bank_mask:0xf bound_ctrl:1
	ds_read_b128 v[36:39], v8 offset:13824
	ds_read_b128 v[40:43], v8 offset:14080
	v_add_f32_dpp v4, v4, v4 row_mirror row_mask:0xf bank_mask:0xf bound_ctrl:1
	v_pk_fma_f32 v[0:1], v[4:5], v[76:77], v[0:1] op_sel_hi:[0,1,1] neg_lo:[1,0,0] neg_hi:[1,0,0]
	v_pk_fma_f32 v[2:3], v[4:5], v[78:79], v[2:3] op_sel_hi:[0,1,1] neg_lo:[1,0,0] neg_hi:[1,0,0]
	ds_read_b128 v[44:47], v8 offset:14336
	ds_read_b128 v[48:51], v8 offset:14592
	ds_read_b128 v[52:55], v8 offset:14848
	ds_read_b32 v56, v9 offset:13824
	s_waitcnt lgkmcnt(14)
	v_pk_mul_f32 v[4:5], v[0:1], v[96:97]
	v_pk_mul_f32 v[6:7], v[0:1], v[108:109]
	v_pk_fma_f32 v[4:5], v[2:3], v[98:99], v[4:5]
	v_pk_fma_f32 v[6:7], v[2:3], v[110:111], v[6:7]
	v_add_f32_e32 v4, v4, v5
	v_add_f32_e32 v6, v6, v7
	v_pk_mul_f32 v[0:1], v[0:1], v[92:93]
	v_add_f32_dpp v4, v4, v4 quad_perm:[1,0,3,2] row_mask:0xf bank_mask:0xf bound_ctrl:1
	v_pk_mul_f32 v[2:3], v[2:3], v[94:95]
	ds_write_b32 v10, v6 offset:7168
	v_add_f32_dpp v4, v4, v4 quad_perm:[2,3,0,1] row_mask:0xf bank_mask:0xf bound_ctrl:1
	v_pk_fma_f32 v[0:1], v[112:113], v[104:105], v[0:1] op_sel_hi:[0,1,1]
	v_pk_fma_f32 v[2:3], v[112:113], v[106:107], v[2:3] op_sel_hi:[0,1,1]
	v_add_f32_dpp v4, v4, v4 row_half_mirror row_mask:0xf bank_mask:0xf bound_ctrl:1
	ds_read_b128 v[68:71], v8 offset:15360
	ds_read_b128 v[72:75], v8 offset:15616
	v_add_f32_dpp v4, v4, v4 row_mirror row_mask:0xf bank_mask:0xf bound_ctrl:1
	v_pk_fma_f32 v[0:1], v[4:5], v[100:101], v[0:1] op_sel_hi:[0,1,1] neg_lo:[1,0,0] neg_hi:[1,0,0]
	v_pk_fma_f32 v[2:3], v[4:5], v[102:103], v[2:3] op_sel_hi:[0,1,1] neg_lo:[1,0,0] neg_hi:[1,0,0]
	ds_read_b128 v[76:79], v8 offset:15872
	ds_read_b128 v[80:83], v8 offset:16128
	ds_read_b128 v[84:87], v8 offset:16384
	ds_read_b32 v88, v9 offset:15360
	s_waitcnt lgkmcnt(14)
	v_pk_mul_f32 v[4:5], v[0:1], v[16:17]
	v_pk_mul_f32 v[6:7], v[0:1], v[28:29]
	v_pk_fma_f32 v[4:5], v[2:3], v[18:19], v[4:5]
	v_pk_fma_f32 v[6:7], v[2:3], v[30:31], v[6:7]
	v_add_f32_e32 v4, v4, v5
	v_add_f32_e32 v6, v6, v7
	v_pk_mul_f32 v[0:1], v[0:1], v[12:13]
	v_add_f32_dpp v4, v4, v4 quad_perm:[1,0,3,2] row_mask:0xf bank_mask:0xf bound_ctrl:1
	v_pk_mul_f32 v[2:3], v[2:3], v[14:15]
	ds_write_b32 v10, v6 offset:8192
	v_add_f32_dpp v4, v4, v4 quad_perm:[2,3,0,1] row_mask:0xf bank_mask:0xf bound_ctrl:1
	v_pk_fma_f32 v[0:1], v[32:33], v[24:25], v[0:1] op_sel_hi:[0,1,1]
	v_pk_fma_f32 v[2:3], v[32:33], v[26:27], v[2:3] op_sel_hi:[0,1,1]
	v_add_f32_dpp v4, v4, v4 row_half_mirror row_mask:0xf bank_mask:0xf bound_ctrl:1
	ds_read_b128 v[92:95], v8 offset:16896
	ds_read_b128 v[96:99], v8 offset:17152
	v_add_f32_dpp v4, v4, v4 row_mirror row_mask:0xf bank_mask:0xf bound_ctrl:1
	v_pk_fma_f32 v[0:1], v[4:5], v[20:21], v[0:1] op_sel_hi:[0,1,1] neg_lo:[1,0,0] neg_hi:[1,0,0]
	v_pk_fma_f32 v[2:3], v[4:5], v[22:23], v[2:3] op_sel_hi:[0,1,1] neg_lo:[1,0,0] neg_hi:[1,0,0]
	ds_read_b128 v[100:103], v8 offset:17408
	ds_read_b128 v[104:107], v8 offset:17664
	ds_read_b128 v[108:111], v8 offset:17920
	ds_read_b32 v112, v9 offset:16896
	s_waitcnt lgkmcnt(14)
	v_pk_mul_f32 v[4:5], v[0:1], v[40:41]
	v_pk_mul_f32 v[6:7], v[0:1], v[52:53]
	v_pk_fma_f32 v[4:5], v[2:3], v[42:43], v[4:5]
	v_pk_fma_f32 v[6:7], v[2:3], v[54:55], v[6:7]
	v_add_f32_e32 v4, v4, v5
	v_add_f32_e32 v6, v6, v7
	v_pk_mul_f32 v[0:1], v[0:1], v[36:37]
	v_add_f32_dpp v4, v4, v4 quad_perm:[1,0,3,2] row_mask:0xf bank_mask:0xf bound_ctrl:1
	v_pk_mul_f32 v[2:3], v[2:3], v[38:39]
	ds_write_b32 v10, v6 offset:9216
	v_add_f32_dpp v4, v4, v4 quad_perm:[2,3,0,1] row_mask:0xf bank_mask:0xf bound_ctrl:1
	v_pk_fma_f32 v[0:1], v[56:57], v[48:49], v[0:1] op_sel_hi:[0,1,1]
	v_pk_fma_f32 v[2:3], v[56:57], v[50:51], v[2:3] op_sel_hi:[0,1,1]
	v_add_f32_dpp v4, v4, v4 row_half_mirror row_mask:0xf bank_mask:0xf bound_ctrl:1
	ds_read_b128 v[12:15], v8 offset:18432
	ds_read_b128 v[16:19], v8 offset:18688
	v_add_f32_dpp v4, v4, v4 row_mirror row_mask:0xf bank_mask:0xf bound_ctrl:1
	v_pk_fma_f32 v[0:1], v[4:5], v[44:45], v[0:1] op_sel_hi:[0,1,1] neg_lo:[1,0,0] neg_hi:[1,0,0]
	v_pk_fma_f32 v[2:3], v[4:5], v[46:47], v[2:3] op_sel_hi:[0,1,1] neg_lo:[1,0,0] neg_hi:[1,0,0]
	ds_read_b128 v[20:23], v8 offset:18944
	ds_read_b128 v[24:27], v8 offset:19200
	ds_read_b128 v[28:31], v8 offset:19456
	ds_read_b32 v32, v9 offset:18432
	s_waitcnt lgkmcnt(14)
	v_pk_mul_f32 v[4:5], v[0:1], v[72:73]
	v_pk_mul_f32 v[6:7], v[0:1], v[84:85]
	v_pk_fma_f32 v[4:5], v[2:3], v[74:75], v[4:5]
	v_pk_fma_f32 v[6:7], v[2:3], v[86:87], v[6:7]
	v_add_f32_e32 v4, v4, v5
	v_add_f32_e32 v6, v6, v7
	v_pk_mul_f32 v[0:1], v[0:1], v[68:69]
	v_add_f32_dpp v4, v4, v4 quad_perm:[1,0,3,2] row_mask:0xf bank_mask:0xf bound_ctrl:1
	v_pk_mul_f32 v[2:3], v[2:3], v[70:71]
	ds_write_b32 v10, v6 offset:10240
	v_add_f32_dpp v4, v4, v4 quad_perm:[2,3,0,1] row_mask:0xf bank_mask:0xf bound_ctrl:1
	v_pk_fma_f32 v[0:1], v[88:89], v[80:81], v[0:1] op_sel_hi:[0,1,1]
	v_pk_fma_f32 v[2:3], v[88:89], v[82:83], v[2:3] op_sel_hi:[0,1,1]
	v_add_f32_dpp v4, v4, v4 row_half_mirror row_mask:0xf bank_mask:0xf bound_ctrl:1
	ds_read_b128 v[36:39], v8 offset:19968
	ds_read_b128 v[40:43], v8 offset:20224
	v_add_f32_dpp v4, v4, v4 row_mirror row_mask:0xf bank_mask:0xf bound_ctrl:1
	v_pk_fma_f32 v[0:1], v[4:5], v[76:77], v[0:1] op_sel_hi:[0,1,1] neg_lo:[1,0,0] neg_hi:[1,0,0]
	v_pk_fma_f32 v[2:3], v[4:5], v[78:79], v[2:3] op_sel_hi:[0,1,1] neg_lo:[1,0,0] neg_hi:[1,0,0]
	ds_read_b128 v[44:47], v8 offset:20480
	ds_read_b128 v[48:51], v8 offset:20736
	ds_read_b128 v[52:55], v8 offset:20992
	ds_read_b32 v56, v9 offset:19968
	s_waitcnt lgkmcnt(14)
	v_pk_mul_f32 v[4:5], v[0:1], v[96:97]
	v_pk_mul_f32 v[6:7], v[0:1], v[108:109]
	v_pk_fma_f32 v[4:5], v[2:3], v[98:99], v[4:5]
	v_pk_fma_f32 v[6:7], v[2:3], v[110:111], v[6:7]
	v_add_f32_e32 v4, v4, v5
	v_add_f32_e32 v6, v6, v7
	v_pk_mul_f32 v[0:1], v[0:1], v[92:93]
	v_add_f32_dpp v4, v4, v4 quad_perm:[1,0,3,2] row_mask:0xf bank_mask:0xf bound_ctrl:1
	v_pk_mul_f32 v[2:3], v[2:3], v[94:95]
	ds_write_b32 v10, v6 offset:11264
	v_add_f32_dpp v4, v4, v4 quad_perm:[2,3,0,1] row_mask:0xf bank_mask:0xf bound_ctrl:1
	v_pk_fma_f32 v[0:1], v[112:113], v[104:105], v[0:1] op_sel_hi:[0,1,1]
	v_pk_fma_f32 v[2:3], v[112:113], v[106:107], v[2:3] op_sel_hi:[0,1,1]
	v_add_f32_dpp v4, v4, v4 row_half_mirror row_mask:0xf bank_mask:0xf bound_ctrl:1
	ds_read_b128 v[68:71], v8 offset:21504
	ds_read_b128 v[72:75], v8 offset:21760
	v_add_f32_dpp v4, v4, v4 row_mirror row_mask:0xf bank_mask:0xf bound_ctrl:1
	v_pk_fma_f32 v[0:1], v[4:5], v[100:101], v[0:1] op_sel_hi:[0,1,1] neg_lo:[1,0,0] neg_hi:[1,0,0]
	v_pk_fma_f32 v[2:3], v[4:5], v[102:103], v[2:3] op_sel_hi:[0,1,1] neg_lo:[1,0,0] neg_hi:[1,0,0]
	ds_read_b128 v[76:79], v8 offset:22016
	ds_read_b128 v[80:83], v8 offset:22272
	ds_read_b128 v[84:87], v8 offset:22528
	ds_read_b32 v88, v9 offset:21504
	s_waitcnt lgkmcnt(14)
	v_pk_mul_f32 v[4:5], v[0:1], v[16:17]
	v_pk_mul_f32 v[6:7], v[0:1], v[28:29]
	v_pk_fma_f32 v[4:5], v[2:3], v[18:19], v[4:5]
	v_pk_fma_f32 v[6:7], v[2:3], v[30:31], v[6:7]
	v_add_f32_e32 v4, v4, v5
	v_add_f32_e32 v6, v6, v7
	v_pk_mul_f32 v[0:1], v[0:1], v[12:13]
	v_add_f32_dpp v4, v4, v4 quad_perm:[1,0,3,2] row_mask:0xf bank_mask:0xf bound_ctrl:1
	v_pk_mul_f32 v[2:3], v[2:3], v[14:15]
	ds_write_b32 v10, v6 offset:12288
	v_add_f32_dpp v4, v4, v4 quad_perm:[2,3,0,1] row_mask:0xf bank_mask:0xf bound_ctrl:1
	v_pk_fma_f32 v[0:1], v[32:33], v[24:25], v[0:1] op_sel_hi:[0,1,1]
	v_pk_fma_f32 v[2:3], v[32:33], v[26:27], v[2:3] op_sel_hi:[0,1,1]
	v_add_f32_dpp v4, v4, v4 row_half_mirror row_mask:0xf bank_mask:0xf bound_ctrl:1
	ds_read_b128 v[92:95], v8 offset:23040
	ds_read_b128 v[96:99], v8 offset:23296
	v_add_f32_dpp v4, v4, v4 row_mirror row_mask:0xf bank_mask:0xf bound_ctrl:1
	v_pk_fma_f32 v[0:1], v[4:5], v[20:21], v[0:1] op_sel_hi:[0,1,1] neg_lo:[1,0,0] neg_hi:[1,0,0]
	v_pk_fma_f32 v[2:3], v[4:5], v[22:23], v[2:3] op_sel_hi:[0,1,1] neg_lo:[1,0,0] neg_hi:[1,0,0]
	ds_read_b128 v[100:103], v8 offset:23552
	ds_read_b128 v[104:107], v8 offset:23808
	ds_read_b128 v[108:111], v8 offset:24064
	ds_read_b32 v112, v9 offset:23040
	s_waitcnt lgkmcnt(14)
	v_pk_mul_f32 v[4:5], v[0:1], v[40:41]
	v_pk_mul_f32 v[6:7], v[0:1], v[52:53]
	v_pk_fma_f32 v[4:5], v[2:3], v[42:43], v[4:5]
	v_pk_fma_f32 v[6:7], v[2:3], v[54:55], v[6:7]
	v_add_f32_e32 v4, v4, v5
	v_add_f32_e32 v6, v6, v7
	v_pk_mul_f32 v[0:1], v[0:1], v[36:37]
	v_add_f32_dpp v4, v4, v4 quad_perm:[1,0,3,2] row_mask:0xf bank_mask:0xf bound_ctrl:1
	v_pk_mul_f32 v[2:3], v[2:3], v[38:39]
	ds_write_b32 v10, v6 offset:13312
	v_add_f32_dpp v4, v4, v4 quad_perm:[2,3,0,1] row_mask:0xf bank_mask:0xf bound_ctrl:1
	v_pk_fma_f32 v[0:1], v[56:57], v[48:49], v[0:1] op_sel_hi:[0,1,1]
	v_pk_fma_f32 v[2:3], v[56:57], v[50:51], v[2:3] op_sel_hi:[0,1,1]
	v_add_f32_dpp v4, v4, v4 row_half_mirror row_mask:0xf bank_mask:0xf bound_ctrl:1
	s_nop 1
	v_add_f32_dpp v4, v4, v4 row_mirror row_mask:0xf bank_mask:0xf bound_ctrl:1
	v_pk_fma_f32 v[0:1], v[4:5], v[44:45], v[0:1] op_sel_hi:[0,1,1] neg_lo:[1,0,0] neg_hi:[1,0,0]
	v_pk_fma_f32 v[2:3], v[4:5], v[46:47], v[2:3] op_sel_hi:[0,1,1] neg_lo:[1,0,0] neg_hi:[1,0,0]
	s_waitcnt lgkmcnt(8)
	v_pk_mul_f32 v[4:5], v[0:1], v[72:73]
	v_pk_mul_f32 v[6:7], v[0:1], v[84:85]
	v_pk_fma_f32 v[4:5], v[2:3], v[74:75], v[4:5]
	v_pk_fma_f32 v[6:7], v[2:3], v[86:87], v[6:7]
	v_add_f32_e32 v4, v4, v5
	v_add_f32_e32 v6, v6, v7
	v_pk_mul_f32 v[0:1], v[0:1], v[68:69]
	v_add_f32_dpp v4, v4, v4 quad_perm:[1,0,3,2] row_mask:0xf bank_mask:0xf bound_ctrl:1
	v_pk_mul_f32 v[2:3], v[2:3], v[70:71]
	ds_write_b32 v10, v6 offset:14336
	v_add_f32_dpp v4, v4, v4 quad_perm:[2,3,0,1] row_mask:0xf bank_mask:0xf bound_ctrl:1
	v_pk_fma_f32 v[0:1], v[88:89], v[80:81], v[0:1] op_sel_hi:[0,1,1]
	v_pk_fma_f32 v[2:3], v[88:89], v[82:83], v[2:3] op_sel_hi:[0,1,1]
	v_add_f32_dpp v4, v4, v4 row_half_mirror row_mask:0xf bank_mask:0xf bound_ctrl:1
	s_nop 1
	v_add_f32_dpp v4, v4, v4 row_mirror row_mask:0xf bank_mask:0xf bound_ctrl:1
	v_pk_fma_f32 v[0:1], v[4:5], v[76:77], v[0:1] op_sel_hi:[0,1,1] neg_lo:[1,0,0] neg_hi:[1,0,0]
	v_pk_fma_f32 v[2:3], v[4:5], v[78:79], v[2:3] op_sel_hi:[0,1,1] neg_lo:[1,0,0] neg_hi:[1,0,0]
	s_waitcnt lgkmcnt(2)
	v_pk_mul_f32 v[4:5], v[0:1], v[96:97]
	v_pk_mul_f32 v[6:7], v[0:1], v[108:109]
	v_pk_fma_f32 v[4:5], v[2:3], v[98:99], v[4:5]
	v_pk_fma_f32 v[6:7], v[2:3], v[110:111], v[6:7]
	v_add_f32_e32 v4, v4, v5
	v_add_f32_e32 v6, v6, v7
	v_pk_mul_f32 v[0:1], v[0:1], v[92:93]
	v_add_f32_dpp v4, v4, v4 quad_perm:[1,0,3,2] row_mask:0xf bank_mask:0xf bound_ctrl:1
	v_pk_mul_f32 v[2:3], v[2:3], v[94:95]
	ds_write_b32 v10, v6 offset:15360
	v_add_f32_dpp v4, v4, v4 quad_perm:[2,3,0,1] row_mask:0xf bank_mask:0xf bound_ctrl:1
	v_pk_fma_f32 v[0:1], v[112:113], v[104:105], v[0:1] op_sel_hi:[0,1,1]
	v_pk_fma_f32 v[2:3], v[112:113], v[106:107], v[2:3] op_sel_hi:[0,1,1]
	v_add_f32_dpp v4, v4, v4 row_half_mirror row_mask:0xf bank_mask:0xf bound_ctrl:1
	s_nop 1
	v_add_f32_dpp v4, v4, v4 row_mirror row_mask:0xf bank_mask:0xf bound_ctrl:1
	v_pk_fma_f32 v[0:1], v[4:5], v[100:101], v[0:1] op_sel_hi:[0,1,1] neg_lo:[1,0,0] neg_hi:[1,0,0]
	v_pk_fma_f32 v[2:3], v[4:5], v[102:103], v[2:3] op_sel_hi:[0,1,1] neg_lo:[1,0,0] neg_hi:[1,0,0]
	s_waitcnt lgkmcnt(0)
	s_barrier
	ds_read_b128 v[12:15], v8 offset:24576
	ds_read_b128 v[16:19], v8 offset:24832
	ds_read_b128 v[20:23], v8 offset:25088
	ds_read_b128 v[24:27], v8 offset:25344
	ds_read_b128 v[28:31], v8 offset:25600
	ds_read_b32 v32, v9 offset:24576
	ds_read_b128 v[36:39], v8 offset:26112
	ds_read_b128 v[40:43], v8 offset:26368
	ds_read_b128 v[44:47], v8 offset:26624
	ds_read_b128 v[48:51], v8 offset:26880
	ds_read_b128 v[52:55], v8 offset:27136
	ds_read_b32 v56, v9 offset:26112
	ds_read_b128 v[68:71], v8 offset:27648
	ds_read_b128 v[72:75], v8 offset:27904
	ds_read_b128 v[76:79], v8 offset:28160
	ds_read_b128 v[80:83], v8 offset:28416
	ds_read_b128 v[84:87], v8 offset:28672
	ds_read_b32 v88, v9 offset:27648
	s_waitcnt lgkmcnt(12)
	v_pk_mul_f32 v[4:5], v[0:1], v[16:17]
	v_pk_mul_f32 v[6:7], v[0:1], v[28:29]
	v_pk_fma_f32 v[4:5], v[2:3], v[18:19], v[4:5]
	v_pk_fma_f32 v[6:7], v[2:3], v[30:31], v[6:7]
	v_add_f32_e32 v4, v4, v5
	v_add_f32_e32 v6, v6, v7
	v_pk_mul_f32 v[0:1], v[0:1], v[12:13]
	v_add_f32_dpp v4, v4, v4 quad_perm:[1,0,3,2] row_mask:0xf bank_mask:0xf bound_ctrl:1
	v_pk_mul_f32 v[2:3], v[2:3], v[14:15]
	ds_write_b32 v10, v6 offset:16384
	v_add_f32_dpp v4, v4, v4 quad_perm:[2,3,0,1] row_mask:0xf bank_mask:0xf bound_ctrl:1
	v_pk_fma_f32 v[0:1], v[32:33], v[24:25], v[0:1] op_sel_hi:[0,1,1]
	v_pk_fma_f32 v[2:3], v[32:33], v[26:27], v[2:3] op_sel_hi:[0,1,1]
	v_add_f32_dpp v4, v4, v4 row_half_mirror row_mask:0xf bank_mask:0xf bound_ctrl:1
	ds_read_b128 v[92:95], v8 offset:29184
	ds_read_b128 v[96:99], v8 offset:29440
	v_add_f32_dpp v4, v4, v4 row_mirror row_mask:0xf bank_mask:0xf bound_ctrl:1
	v_pk_fma_f32 v[0:1], v[4:5], v[20:21], v[0:1] op_sel_hi:[0,1,1] neg_lo:[1,0,0] neg_hi:[1,0,0]
	v_pk_fma_f32 v[2:3], v[4:5], v[22:23], v[2:3] op_sel_hi:[0,1,1] neg_lo:[1,0,0] neg_hi:[1,0,0]
	ds_read_b128 v[100:103], v8 offset:29696
	ds_read_b128 v[104:107], v8 offset:29952
	ds_read_b128 v[108:111], v8 offset:30208
	ds_read_b32 v112, v9 offset:29184
	s_waitcnt lgkmcnt(13)
	v_pk_mul_f32 v[4:5], v[0:1], v[40:41]
	v_pk_mul_f32 v[6:7], v[0:1], v[52:53]
	v_pk_fma_f32 v[4:5], v[2:3], v[42:43], v[4:5]
	v_pk_fma_f32 v[6:7], v[2:3], v[54:55], v[6:7]
	v_add_f32_e32 v4, v4, v5
	v_add_f32_e32 v6, v6, v7
	v_pk_mul_f32 v[0:1], v[0:1], v[36:37]
	v_add_f32_dpp v4, v4, v4 quad_perm:[1,0,3,2] row_mask:0xf bank_mask:0xf bound_ctrl:1
	v_pk_mul_f32 v[2:3], v[2:3], v[38:39]
	ds_write_b32 v10, v6 offset:17408
	v_add_f32_dpp v4, v4, v4 quad_perm:[2,3,0,1] row_mask:0xf bank_mask:0xf bound_ctrl:1
	v_pk_fma_f32 v[0:1], v[56:57], v[48:49], v[0:1] op_sel_hi:[0,1,1]
	v_pk_fma_f32 v[2:3], v[56:57], v[50:51], v[2:3] op_sel_hi:[0,1,1]
	v_add_f32_dpp v4, v4, v4 row_half_mirror row_mask:0xf bank_mask:0xf bound_ctrl:1
	ds_read_b128 v[12:15], v8 offset:30720
	ds_read_b128 v[16:19], v8 offset:30976
	v_add_f32_dpp v4, v4, v4 row_mirror row_mask:0xf bank_mask:0xf bound_ctrl:1
	v_pk_fma_f32 v[0:1], v[4:5], v[44:45], v[0:1] op_sel_hi:[0,1,1] neg_lo:[1,0,0] neg_hi:[1,0,0]
	v_pk_fma_f32 v[2:3], v[4:5], v[46:47], v[2:3] op_sel_hi:[0,1,1] neg_lo:[1,0,0] neg_hi:[1,0,0]
	ds_read_b128 v[20:23], v8 offset:31232
	ds_read_b128 v[24:27], v8 offset:31488
	ds_read_b128 v[28:31], v8 offset:31744
	ds_read_b32 v32, v9 offset:30720
	s_waitcnt lgkmcnt(14)
	v_pk_mul_f32 v[4:5], v[0:1], v[72:73]
	v_pk_mul_f32 v[6:7], v[0:1], v[84:85]
	v_pk_fma_f32 v[4:5], v[2:3], v[74:75], v[4:5]
	v_pk_fma_f32 v[6:7], v[2:3], v[86:87], v[6:7]
	v_add_f32_e32 v4, v4, v5
	v_add_f32_e32 v6, v6, v7
	v_pk_mul_f32 v[0:1], v[0:1], v[68:69]
	v_add_f32_dpp v4, v4, v4 quad_perm:[1,0,3,2] row_mask:0xf bank_mask:0xf bound_ctrl:1
	v_pk_mul_f32 v[2:3], v[2:3], v[70:71]
	ds_write_b32 v10, v6 offset:18432
	v_add_f32_dpp v4, v4, v4 quad_perm:[2,3,0,1] row_mask:0xf bank_mask:0xf bound_ctrl:1
	v_pk_fma_f32 v[0:1], v[88:89], v[80:81], v[0:1] op_sel_hi:[0,1,1]
	v_pk_fma_f32 v[2:3], v[88:89], v[82:83], v[2:3] op_sel_hi:[0,1,1]
	v_add_f32_dpp v4, v4, v4 row_half_mirror row_mask:0xf bank_mask:0xf bound_ctrl:1
	ds_read_b128 v[36:39], v8 offset:32256
	ds_read_b128 v[40:43], v8 offset:32512
	v_add_f32_dpp v4, v4, v4 row_mirror row_mask:0xf bank_mask:0xf bound_ctrl:1
	v_pk_fma_f32 v[0:1], v[4:5], v[76:77], v[0:1] op_sel_hi:[0,1,1] neg_lo:[1,0,0] neg_hi:[1,0,0]
	v_pk_fma_f32 v[2:3], v[4:5], v[78:79], v[2:3] op_sel_hi:[0,1,1] neg_lo:[1,0,0] neg_hi:[1,0,0]
	ds_read_b128 v[44:47], v8 offset:32768
	ds_read_b128 v[48:51], v8 offset:33024
	ds_read_b128 v[52:55], v8 offset:33280
	ds_read_b32 v56, v9 offset:32256
	s_waitcnt lgkmcnt(14)
	v_pk_mul_f32 v[4:5], v[0:1], v[96:97]
	v_pk_mul_f32 v[6:7], v[0:1], v[108:109]
	v_pk_fma_f32 v[4:5], v[2:3], v[98:99], v[4:5]
	v_pk_fma_f32 v[6:7], v[2:3], v[110:111], v[6:7]
	v_add_f32_e32 v4, v4, v5
	v_add_f32_e32 v6, v6, v7
	v_pk_mul_f32 v[0:1], v[0:1], v[92:93]
	v_add_f32_dpp v4, v4, v4 quad_perm:[1,0,3,2] row_mask:0xf bank_mask:0xf bound_ctrl:1
	v_pk_mul_f32 v[2:3], v[2:3], v[94:95]
	ds_write_b32 v10, v6 offset:19456
	v_add_f32_dpp v4, v4, v4 quad_perm:[2,3,0,1] row_mask:0xf bank_mask:0xf bound_ctrl:1
	v_pk_fma_f32 v[0:1], v[112:113], v[104:105], v[0:1] op_sel_hi:[0,1,1]
	v_pk_fma_f32 v[2:3], v[112:113], v[106:107], v[2:3] op_sel_hi:[0,1,1]
	v_add_f32_dpp v4, v4, v4 row_half_mirror row_mask:0xf bank_mask:0xf bound_ctrl:1
	ds_read_b128 v[68:71], v8 offset:33792
	ds_read_b128 v[72:75], v8 offset:34048
	v_add_f32_dpp v4, v4, v4 row_mirror row_mask:0xf bank_mask:0xf bound_ctrl:1
	v_pk_fma_f32 v[0:1], v[4:5], v[100:101], v[0:1] op_sel_hi:[0,1,1] neg_lo:[1,0,0] neg_hi:[1,0,0]
	v_pk_fma_f32 v[2:3], v[4:5], v[102:103], v[2:3] op_sel_hi:[0,1,1] neg_lo:[1,0,0] neg_hi:[1,0,0]
	ds_read_b128 v[76:79], v8 offset:34304
	ds_read_b128 v[80:83], v8 offset:34560
	ds_read_b128 v[84:87], v8 offset:34816
	ds_read_b32 v88, v9 offset:33792
	s_waitcnt lgkmcnt(14)
	v_pk_mul_f32 v[4:5], v[0:1], v[16:17]
	v_pk_mul_f32 v[6:7], v[0:1], v[28:29]
	v_pk_fma_f32 v[4:5], v[2:3], v[18:19], v[4:5]
	v_pk_fma_f32 v[6:7], v[2:3], v[30:31], v[6:7]
	v_add_f32_e32 v4, v4, v5
	v_add_f32_e32 v6, v6, v7
	v_pk_mul_f32 v[0:1], v[0:1], v[12:13]
	v_add_f32_dpp v4, v4, v4 quad_perm:[1,0,3,2] row_mask:0xf bank_mask:0xf bound_ctrl:1
	v_pk_mul_f32 v[2:3], v[2:3], v[14:15]
	ds_write_b32 v10, v6 offset:20480
	v_add_f32_dpp v4, v4, v4 quad_perm:[2,3,0,1] row_mask:0xf bank_mask:0xf bound_ctrl:1
	v_pk_fma_f32 v[0:1], v[32:33], v[24:25], v[0:1] op_sel_hi:[0,1,1]
	v_pk_fma_f32 v[2:3], v[32:33], v[26:27], v[2:3] op_sel_hi:[0,1,1]
	v_add_f32_dpp v4, v4, v4 row_half_mirror row_mask:0xf bank_mask:0xf bound_ctrl:1
	ds_read_b128 v[92:95], v8 offset:35328
	ds_read_b128 v[96:99], v8 offset:35584
	v_add_f32_dpp v4, v4, v4 row_mirror row_mask:0xf bank_mask:0xf bound_ctrl:1
	v_pk_fma_f32 v[0:1], v[4:5], v[20:21], v[0:1] op_sel_hi:[0,1,1] neg_lo:[1,0,0] neg_hi:[1,0,0]
	v_pk_fma_f32 v[2:3], v[4:5], v[22:23], v[2:3] op_sel_hi:[0,1,1] neg_lo:[1,0,0] neg_hi:[1,0,0]
	ds_read_b128 v[100:103], v8 offset:35840
	ds_read_b128 v[104:107], v8 offset:36096
	ds_read_b128 v[108:111], v8 offset:36352
	ds_read_b32 v112, v9 offset:35328
	s_waitcnt lgkmcnt(14)
	v_pk_mul_f32 v[4:5], v[0:1], v[40:41]
	v_pk_mul_f32 v[6:7], v[0:1], v[52:53]
	v_pk_fma_f32 v[4:5], v[2:3], v[42:43], v[4:5]
	v_pk_fma_f32 v[6:7], v[2:3], v[54:55], v[6:7]
	v_add_f32_e32 v4, v4, v5
	v_add_f32_e32 v6, v6, v7
	v_pk_mul_f32 v[0:1], v[0:1], v[36:37]
	v_add_f32_dpp v4, v4, v4 quad_perm:[1,0,3,2] row_mask:0xf bank_mask:0xf bound_ctrl:1
	v_pk_mul_f32 v[2:3], v[2:3], v[38:39]
	ds_write_b32 v10, v6 offset:21504
	v_add_f32_dpp v4, v4, v4 quad_perm:[2,3,0,1] row_mask:0xf bank_mask:0xf bound_ctrl:1
	v_pk_fma_f32 v[0:1], v[56:57], v[48:49], v[0:1] op_sel_hi:[0,1,1]
	v_pk_fma_f32 v[2:3], v[56:57], v[50:51], v[2:3] op_sel_hi:[0,1,1]
	v_add_f32_dpp v4, v4, v4 row_half_mirror row_mask:0xf bank_mask:0xf bound_ctrl:1
	ds_read_b128 v[12:15], v8 offset:36864
	ds_read_b128 v[16:19], v8 offset:37120
	v_add_f32_dpp v4, v4, v4 row_mirror row_mask:0xf bank_mask:0xf bound_ctrl:1
	v_pk_fma_f32 v[0:1], v[4:5], v[44:45], v[0:1] op_sel_hi:[0,1,1] neg_lo:[1,0,0] neg_hi:[1,0,0]
	v_pk_fma_f32 v[2:3], v[4:5], v[46:47], v[2:3] op_sel_hi:[0,1,1] neg_lo:[1,0,0] neg_hi:[1,0,0]
	ds_read_b128 v[20:23], v8 offset:37376
	ds_read_b128 v[24:27], v8 offset:37632
	ds_read_b128 v[28:31], v8 offset:37888
	ds_read_b32 v32, v9 offset:36864
	s_waitcnt lgkmcnt(14)
	v_pk_mul_f32 v[4:5], v[0:1], v[72:73]
	v_pk_mul_f32 v[6:7], v[0:1], v[84:85]
	v_pk_fma_f32 v[4:5], v[2:3], v[74:75], v[4:5]
	v_pk_fma_f32 v[6:7], v[2:3], v[86:87], v[6:7]
	v_add_f32_e32 v4, v4, v5
	v_add_f32_e32 v6, v6, v7
	v_pk_mul_f32 v[0:1], v[0:1], v[68:69]
	v_add_f32_dpp v4, v4, v4 quad_perm:[1,0,3,2] row_mask:0xf bank_mask:0xf bound_ctrl:1
	v_pk_mul_f32 v[2:3], v[2:3], v[70:71]
	ds_write_b32 v10, v6 offset:22528
	v_add_f32_dpp v4, v4, v4 quad_perm:[2,3,0,1] row_mask:0xf bank_mask:0xf bound_ctrl:1
	v_pk_fma_f32 v[0:1], v[88:89], v[80:81], v[0:1] op_sel_hi:[0,1,1]
	v_pk_fma_f32 v[2:3], v[88:89], v[82:83], v[2:3] op_sel_hi:[0,1,1]
	v_add_f32_dpp v4, v4, v4 row_half_mirror row_mask:0xf bank_mask:0xf bound_ctrl:1
	ds_read_b128 v[36:39], v8 offset:38400
	ds_read_b128 v[40:43], v8 offset:38656
	v_add_f32_dpp v4, v4, v4 row_mirror row_mask:0xf bank_mask:0xf bound_ctrl:1
	v_pk_fma_f32 v[0:1], v[4:5], v[76:77], v[0:1] op_sel_hi:[0,1,1] neg_lo:[1,0,0] neg_hi:[1,0,0]
	v_pk_fma_f32 v[2:3], v[4:5], v[78:79], v[2:3] op_sel_hi:[0,1,1] neg_lo:[1,0,0] neg_hi:[1,0,0]
	ds_read_b128 v[44:47], v8 offset:38912
	ds_read_b128 v[48:51], v8 offset:39168
	ds_read_b128 v[52:55], v8 offset:39424
	ds_read_b32 v56, v9 offset:38400
	s_waitcnt lgkmcnt(14)
	v_pk_mul_f32 v[4:5], v[0:1], v[96:97]
	v_pk_mul_f32 v[6:7], v[0:1], v[108:109]
	v_pk_fma_f32 v[4:5], v[2:3], v[98:99], v[4:5]
	v_pk_fma_f32 v[6:7], v[2:3], v[110:111], v[6:7]
	v_add_f32_e32 v4, v4, v5
	v_add_f32_e32 v6, v6, v7
	v_pk_mul_f32 v[0:1], v[0:1], v[92:93]
	v_add_f32_dpp v4, v4, v4 quad_perm:[1,0,3,2] row_mask:0xf bank_mask:0xf bound_ctrl:1
	v_pk_mul_f32 v[2:3], v[2:3], v[94:95]
	ds_write_b32 v10, v6 offset:23552
	v_add_f32_dpp v4, v4, v4 quad_perm:[2,3,0,1] row_mask:0xf bank_mask:0xf bound_ctrl:1
	v_pk_fma_f32 v[0:1], v[112:113], v[104:105], v[0:1] op_sel_hi:[0,1,1]
	v_pk_fma_f32 v[2:3], v[112:113], v[106:107], v[2:3] op_sel_hi:[0,1,1]
	v_add_f32_dpp v4, v4, v4 row_half_mirror row_mask:0xf bank_mask:0xf bound_ctrl:1
	ds_read_b128 v[68:71], v8 offset:39936
	ds_read_b128 v[72:75], v8 offset:40192
	v_add_f32_dpp v4, v4, v4 row_mirror row_mask:0xf bank_mask:0xf bound_ctrl:1
	v_pk_fma_f32 v[0:1], v[4:5], v[100:101], v[0:1] op_sel_hi:[0,1,1] neg_lo:[1,0,0] neg_hi:[1,0,0]
	v_pk_fma_f32 v[2:3], v[4:5], v[102:103], v[2:3] op_sel_hi:[0,1,1] neg_lo:[1,0,0] neg_hi:[1,0,0]
	ds_read_b128 v[76:79], v8 offset:40448
	ds_read_b128 v[80:83], v8 offset:40704
	ds_read_b128 v[84:87], v8 offset:40960
	ds_read_b32 v88, v9 offset:39936
	s_waitcnt lgkmcnt(14)
	v_pk_mul_f32 v[4:5], v[0:1], v[16:17]
	v_pk_mul_f32 v[6:7], v[0:1], v[28:29]
	v_pk_fma_f32 v[4:5], v[2:3], v[18:19], v[4:5]
	v_pk_fma_f32 v[6:7], v[2:3], v[30:31], v[6:7]
	v_add_f32_e32 v4, v4, v5
	v_add_f32_e32 v6, v6, v7
	v_pk_mul_f32 v[0:1], v[0:1], v[12:13]
	v_add_f32_dpp v4, v4, v4 quad_perm:[1,0,3,2] row_mask:0xf bank_mask:0xf bound_ctrl:1
	v_pk_mul_f32 v[2:3], v[2:3], v[14:15]
	ds_write_b32 v10, v6 offset:24576
	v_add_f32_dpp v4, v4, v4 quad_perm:[2,3,0,1] row_mask:0xf bank_mask:0xf bound_ctrl:1
	v_pk_fma_f32 v[0:1], v[32:33], v[24:25], v[0:1] op_sel_hi:[0,1,1]
	v_pk_fma_f32 v[2:3], v[32:33], v[26:27], v[2:3] op_sel_hi:[0,1,1]
	v_add_f32_dpp v4, v4, v4 row_half_mirror row_mask:0xf bank_mask:0xf bound_ctrl:1
	ds_read_b128 v[92:95], v8 offset:41472
	ds_read_b128 v[96:99], v8 offset:41728
	v_add_f32_dpp v4, v4, v4 row_mirror row_mask:0xf bank_mask:0xf bound_ctrl:1
	v_pk_fma_f32 v[0:1], v[4:5], v[20:21], v[0:1] op_sel_hi:[0,1,1] neg_lo:[1,0,0] neg_hi:[1,0,0]
	v_pk_fma_f32 v[2:3], v[4:5], v[22:23], v[2:3] op_sel_hi:[0,1,1] neg_lo:[1,0,0] neg_hi:[1,0,0]
	ds_read_b128 v[100:103], v8 offset:41984
	ds_read_b128 v[104:107], v8 offset:42240
	ds_read_b128 v[108:111], v8 offset:42496
	ds_read_b32 v112, v9 offset:41472
	s_waitcnt lgkmcnt(14)
	v_pk_mul_f32 v[4:5], v[0:1], v[40:41]
	v_pk_mul_f32 v[6:7], v[0:1], v[52:53]
	v_pk_fma_f32 v[4:5], v[2:3], v[42:43], v[4:5]
	v_pk_fma_f32 v[6:7], v[2:3], v[54:55], v[6:7]
	v_add_f32_e32 v4, v4, v5
	v_add_f32_e32 v6, v6, v7
	v_pk_mul_f32 v[0:1], v[0:1], v[36:37]
	v_add_f32_dpp v4, v4, v4 quad_perm:[1,0,3,2] row_mask:0xf bank_mask:0xf bound_ctrl:1
	v_pk_mul_f32 v[2:3], v[2:3], v[38:39]
	ds_write_b32 v10, v6 offset:25600
	v_add_f32_dpp v4, v4, v4 quad_perm:[2,3,0,1] row_mask:0xf bank_mask:0xf bound_ctrl:1
	v_pk_fma_f32 v[0:1], v[56:57], v[48:49], v[0:1] op_sel_hi:[0,1,1]
	v_pk_fma_f32 v[2:3], v[56:57], v[50:51], v[2:3] op_sel_hi:[0,1,1]
	v_add_f32_dpp v4, v4, v4 row_half_mirror row_mask:0xf bank_mask:0xf bound_ctrl:1
	ds_read_b128 v[12:15], v8 offset:43008
	ds_read_b128 v[16:19], v8 offset:43264
	v_add_f32_dpp v4, v4, v4 row_mirror row_mask:0xf bank_mask:0xf bound_ctrl:1
	v_pk_fma_f32 v[0:1], v[4:5], v[44:45], v[0:1] op_sel_hi:[0,1,1] neg_lo:[1,0,0] neg_hi:[1,0,0]
	v_pk_fma_f32 v[2:3], v[4:5], v[46:47], v[2:3] op_sel_hi:[0,1,1] neg_lo:[1,0,0] neg_hi:[1,0,0]
	ds_read_b128 v[20:23], v8 offset:43520
	ds_read_b128 v[24:27], v8 offset:43776
	ds_read_b128 v[28:31], v8 offset:44032
	ds_read_b32 v32, v9 offset:43008
	s_waitcnt lgkmcnt(14)
	v_pk_mul_f32 v[4:5], v[0:1], v[72:73]
	v_pk_mul_f32 v[6:7], v[0:1], v[84:85]
	v_pk_fma_f32 v[4:5], v[2:3], v[74:75], v[4:5]
	v_pk_fma_f32 v[6:7], v[2:3], v[86:87], v[6:7]
	v_add_f32_e32 v4, v4, v5
	v_add_f32_e32 v6, v6, v7
	v_pk_mul_f32 v[0:1], v[0:1], v[68:69]
	v_add_f32_dpp v4, v4, v4 quad_perm:[1,0,3,2] row_mask:0xf bank_mask:0xf bound_ctrl:1
	v_pk_mul_f32 v[2:3], v[2:3], v[70:71]
	ds_write_b32 v10, v6 offset:26624
	v_add_f32_dpp v4, v4, v4 quad_perm:[2,3,0,1] row_mask:0xf bank_mask:0xf bound_ctrl:1
	v_pk_fma_f32 v[0:1], v[88:89], v[80:81], v[0:1] op_sel_hi:[0,1,1]
	v_pk_fma_f32 v[2:3], v[88:89], v[82:83], v[2:3] op_sel_hi:[0,1,1]
	v_add_f32_dpp v4, v4, v4 row_half_mirror row_mask:0xf bank_mask:0xf bound_ctrl:1
	ds_read_b128 v[36:39], v8 offset:44544
	ds_read_b128 v[40:43], v8 offset:44800
	v_add_f32_dpp v4, v4, v4 row_mirror row_mask:0xf bank_mask:0xf bound_ctrl:1
	v_pk_fma_f32 v[0:1], v[4:5], v[76:77], v[0:1] op_sel_hi:[0,1,1] neg_lo:[1,0,0] neg_hi:[1,0,0]
	v_pk_fma_f32 v[2:3], v[4:5], v[78:79], v[2:3] op_sel_hi:[0,1,1] neg_lo:[1,0,0] neg_hi:[1,0,0]
	ds_read_b128 v[44:47], v8 offset:45056
	ds_read_b128 v[48:51], v8 offset:45312
	ds_read_b128 v[52:55], v8 offset:45568
	ds_read_b32 v56, v9 offset:44544
	s_waitcnt lgkmcnt(14)
	v_pk_mul_f32 v[4:5], v[0:1], v[96:97]
	v_pk_mul_f32 v[6:7], v[0:1], v[108:109]
	v_pk_fma_f32 v[4:5], v[2:3], v[98:99], v[4:5]
	v_pk_fma_f32 v[6:7], v[2:3], v[110:111], v[6:7]
	v_add_f32_e32 v4, v4, v5
	v_add_f32_e32 v6, v6, v7
	v_pk_mul_f32 v[0:1], v[0:1], v[92:93]
	v_add_f32_dpp v4, v4, v4 quad_perm:[1,0,3,2] row_mask:0xf bank_mask:0xf bound_ctrl:1
	v_pk_mul_f32 v[2:3], v[2:3], v[94:95]
	ds_write_b32 v10, v6 offset:27648
	v_add_f32_dpp v4, v4, v4 quad_perm:[2,3,0,1] row_mask:0xf bank_mask:0xf bound_ctrl:1
	v_pk_fma_f32 v[0:1], v[112:113], v[104:105], v[0:1] op_sel_hi:[0,1,1]
	v_pk_fma_f32 v[2:3], v[112:113], v[106:107], v[2:3] op_sel_hi:[0,1,1]
	v_add_f32_dpp v4, v4, v4 row_half_mirror row_mask:0xf bank_mask:0xf bound_ctrl:1
	ds_read_b128 v[68:71], v8 offset:46080
	ds_read_b128 v[72:75], v8 offset:46336
	v_add_f32_dpp v4, v4, v4 row_mirror row_mask:0xf bank_mask:0xf bound_ctrl:1
	v_pk_fma_f32 v[0:1], v[4:5], v[100:101], v[0:1] op_sel_hi:[0,1,1] neg_lo:[1,0,0] neg_hi:[1,0,0]
	v_pk_fma_f32 v[2:3], v[4:5], v[102:103], v[2:3] op_sel_hi:[0,1,1] neg_lo:[1,0,0] neg_hi:[1,0,0]
	ds_read_b128 v[76:79], v8 offset:46592
	ds_read_b128 v[80:83], v8 offset:46848
	ds_read_b128 v[84:87], v8 offset:47104
	ds_read_b32 v88, v9 offset:46080
	s_waitcnt lgkmcnt(14)
	v_pk_mul_f32 v[4:5], v[0:1], v[16:17]
	v_pk_mul_f32 v[6:7], v[0:1], v[28:29]
	v_pk_fma_f32 v[4:5], v[2:3], v[18:19], v[4:5]
	v_pk_fma_f32 v[6:7], v[2:3], v[30:31], v[6:7]
	v_add_f32_e32 v4, v4, v5
	v_add_f32_e32 v6, v6, v7
	v_pk_mul_f32 v[0:1], v[0:1], v[12:13]
	v_add_f32_dpp v4, v4, v4 quad_perm:[1,0,3,2] row_mask:0xf bank_mask:0xf bound_ctrl:1
	v_pk_mul_f32 v[2:3], v[2:3], v[14:15]
	ds_write_b32 v10, v6 offset:28672
	v_add_f32_dpp v4, v4, v4 quad_perm:[2,3,0,1] row_mask:0xf bank_mask:0xf bound_ctrl:1
	v_pk_fma_f32 v[0:1], v[32:33], v[24:25], v[0:1] op_sel_hi:[0,1,1]
	v_pk_fma_f32 v[2:3], v[32:33], v[26:27], v[2:3] op_sel_hi:[0,1,1]
	v_add_f32_dpp v4, v4, v4 row_half_mirror row_mask:0xf bank_mask:0xf bound_ctrl:1
	ds_read_b128 v[92:95], v8 offset:47616
	ds_read_b128 v[96:99], v8 offset:47872
	v_add_f32_dpp v4, v4, v4 row_mirror row_mask:0xf bank_mask:0xf bound_ctrl:1
	v_pk_fma_f32 v[0:1], v[4:5], v[20:21], v[0:1] op_sel_hi:[0,1,1] neg_lo:[1,0,0] neg_hi:[1,0,0]
	v_pk_fma_f32 v[2:3], v[4:5], v[22:23], v[2:3] op_sel_hi:[0,1,1] neg_lo:[1,0,0] neg_hi:[1,0,0]
	ds_read_b128 v[100:103], v8 offset:48128
	ds_read_b128 v[104:107], v8 offset:48384
	ds_read_b128 v[108:111], v8 offset:48640
	ds_read_b32 v112, v9 offset:47616
	s_waitcnt lgkmcnt(14)
	v_pk_mul_f32 v[4:5], v[0:1], v[40:41]
	v_pk_mul_f32 v[6:7], v[0:1], v[52:53]
	v_pk_fma_f32 v[4:5], v[2:3], v[42:43], v[4:5]
	v_pk_fma_f32 v[6:7], v[2:3], v[54:55], v[6:7]
	v_add_f32_e32 v4, v4, v5
	v_add_f32_e32 v6, v6, v7
	v_pk_mul_f32 v[0:1], v[0:1], v[36:37]
	v_add_f32_dpp v4, v4, v4 quad_perm:[1,0,3,2] row_mask:0xf bank_mask:0xf bound_ctrl:1
	v_pk_mul_f32 v[2:3], v[2:3], v[38:39]
	ds_write_b32 v10, v6 offset:29696
	v_add_f32_dpp v4, v4, v4 quad_perm:[2,3,0,1] row_mask:0xf bank_mask:0xf bound_ctrl:1
	v_pk_fma_f32 v[0:1], v[56:57], v[48:49], v[0:1] op_sel_hi:[0,1,1]
	v_pk_fma_f32 v[2:3], v[56:57], v[50:51], v[2:3] op_sel_hi:[0,1,1]
	v_add_f32_dpp v4, v4, v4 row_half_mirror row_mask:0xf bank_mask:0xf bound_ctrl:1
	s_nop 1
	v_add_f32_dpp v4, v4, v4 row_mirror row_mask:0xf bank_mask:0xf bound_ctrl:1
	v_pk_fma_f32 v[0:1], v[4:5], v[44:45], v[0:1] op_sel_hi:[0,1,1] neg_lo:[1,0,0] neg_hi:[1,0,0]
	v_pk_fma_f32 v[2:3], v[4:5], v[46:47], v[2:3] op_sel_hi:[0,1,1] neg_lo:[1,0,0] neg_hi:[1,0,0]
	s_waitcnt lgkmcnt(8)
	v_pk_mul_f32 v[4:5], v[0:1], v[72:73]
	v_pk_mul_f32 v[6:7], v[0:1], v[84:85]
	v_pk_fma_f32 v[4:5], v[2:3], v[74:75], v[4:5]
	v_pk_fma_f32 v[6:7], v[2:3], v[86:87], v[6:7]
	v_add_f32_e32 v4, v4, v5
	v_add_f32_e32 v6, v6, v7
	v_pk_mul_f32 v[0:1], v[0:1], v[68:69]
	v_add_f32_dpp v4, v4, v4 quad_perm:[1,0,3,2] row_mask:0xf bank_mask:0xf bound_ctrl:1
	v_pk_mul_f32 v[2:3], v[2:3], v[70:71]
	ds_write_b32 v10, v6 offset:30720
	v_add_f32_dpp v4, v4, v4 quad_perm:[2,3,0,1] row_mask:0xf bank_mask:0xf bound_ctrl:1
	v_pk_fma_f32 v[0:1], v[88:89], v[80:81], v[0:1] op_sel_hi:[0,1,1]
	v_pk_fma_f32 v[2:3], v[88:89], v[82:83], v[2:3] op_sel_hi:[0,1,1]
	v_add_f32_dpp v4, v4, v4 row_half_mirror row_mask:0xf bank_mask:0xf bound_ctrl:1
	s_nop 1
	v_add_f32_dpp v4, v4, v4 row_mirror row_mask:0xf bank_mask:0xf bound_ctrl:1
	v_pk_fma_f32 v[0:1], v[4:5], v[76:77], v[0:1] op_sel_hi:[0,1,1] neg_lo:[1,0,0] neg_hi:[1,0,0]
	v_pk_fma_f32 v[2:3], v[4:5], v[78:79], v[2:3] op_sel_hi:[0,1,1] neg_lo:[1,0,0] neg_hi:[1,0,0]
	s_waitcnt lgkmcnt(2)
	v_pk_mul_f32 v[4:5], v[0:1], v[96:97]
	v_pk_mul_f32 v[6:7], v[0:1], v[108:109]
	v_pk_fma_f32 v[4:5], v[2:3], v[98:99], v[4:5]
	v_pk_fma_f32 v[6:7], v[2:3], v[110:111], v[6:7]
	v_add_f32_e32 v4, v4, v5
	v_add_f32_e32 v6, v6, v7
	v_pk_mul_f32 v[0:1], v[0:1], v[92:93]
	v_add_f32_dpp v4, v4, v4 quad_perm:[1,0,3,2] row_mask:0xf bank_mask:0xf bound_ctrl:1
	v_pk_mul_f32 v[2:3], v[2:3], v[94:95]
	ds_write_b32 v10, v6 offset:31744
	v_add_f32_dpp v4, v4, v4 quad_perm:[2,3,0,1] row_mask:0xf bank_mask:0xf bound_ctrl:1
	v_pk_fma_f32 v[0:1], v[112:113], v[104:105], v[0:1] op_sel_hi:[0,1,1]
	v_pk_fma_f32 v[2:3], v[112:113], v[106:107], v[2:3] op_sel_hi:[0,1,1]
	v_add_f32_dpp v4, v4, v4 row_half_mirror row_mask:0xf bank_mask:0xf bound_ctrl:1
	s_nop 1
	v_add_f32_dpp v4, v4, v4 row_mirror row_mask:0xf bank_mask:0xf bound_ctrl:1
	v_pk_fma_f32 v[0:1], v[4:5], v[100:101], v[0:1] op_sel_hi:[0,1,1] neg_lo:[1,0,0] neg_hi:[1,0,0]
	v_pk_fma_f32 v[2:3], v[4:5], v[102:103], v[2:3] op_sel_hi:[0,1,1] neg_lo:[1,0,0] neg_hi:[1,0,0]
	s_waitcnt lgkmcnt(0)
	s_barrier
	ds_read_b128 v[12:15], v8 offset:0
	ds_read_b128 v[16:19], v8 offset:256
	ds_read_b128 v[20:23], v8 offset:512
	ds_read_b128 v[24:27], v8 offset:768
	ds_read_b128 v[28:31], v8 offset:1024
	ds_read_b32 v32, v9 offset:0
	ds_read_b128 v[36:39], v8 offset:1536
	ds_read_b128 v[40:43], v8 offset:1792
	ds_read_b128 v[44:47], v8 offset:2048
	ds_read_b128 v[48:51], v8 offset:2304
	ds_read_b128 v[52:55], v8 offset:2560
	ds_read_b32 v56, v9 offset:1536
	ds_read_b128 v[68:71], v8 offset:3072
	ds_read_b128 v[72:75], v8 offset:3328
	ds_read_b128 v[76:79], v8 offset:3584
	ds_read_b128 v[80:83], v8 offset:3840
	ds_read_b128 v[84:87], v8 offset:4096
	ds_read_b32 v88, v9 offset:3072
	s_sub_u32 s34, s34, 1
	s_cmp_lg_u32 s34, 0
	s_cbranch_scc1 .Lb2_scan_loop
	s_setprio 0
	s_waitcnt lgkmcnt(0)
	global_store_dwordx4 v11, v[0:3], s[40:41]
	s_branch .Lb2_u_next
.Lb2_loader:
	v_add_u32_e32 v61, 0xffffff00, v133
	v_lshrrev_b32_e32 v62, 5, v61
	v_mul_u32_u24_e32 v48, 0x600, v62
	v_and_b32_e32 v63, 31, v61
	v_lshl_add_u32 v48, v63, 4, v48
	v_add_u32_e32 v49, 0x3000, v48
	v_lshlrev_b32_e32 v51, 6, v61
	v_add_u32_e32 v51, 0xc000, v51
	v_lshrrev_b32_e32 v62, 4, v61
	v_lshlrev_b32_e32 v60, 11, v62
	v_and_b32_e32 v63, 15, v61
	v_lshl_add_u32 v60, v63, 2, v60
	s_lshr_b32 s21, s20, 3
	s_lshl_b32 s21, s21, 22
	s_and_b32 s23, s20, 7
	s_lshl_b32 s23, s23, 8
	s_add_i32 s21, s21, s23
	s_lshl_b32 s23, s33, 6
	s_add_i32 s21, s21, s23
	s_add_u32 s21, s21, 0x19314000
	s_add_u32 s36, s94, s21
	s_addc_u32 s37, s95, 0
	s_mov_b32 s38, 0x55555555
	s_mov_b32 s39, 0x55555555
	s_movk_i32 s34, 0x40
	s_mov_b32 s35, 0
	global_load_dwordx4 v[0:3], v48, s[28:29]
	global_load_dwordx4 v[4:7], v48, s[28:29] offset:512
	global_load_dwordx4 v[8:11], v48, s[28:29] offset:1024
	global_load_dwordx4 v[12:15], v49, s[28:29]
	global_load_dwordx4 v[16:19], v49, s[28:29] offset:512
	global_load_dwordx4 v[20:23], v49, s[28:29] offset:1024
	s_add_u32 s28, s28, 0x6000
	s_addc_u32 s29, s29, 0
	global_load_dwordx4 v[24:27], v48, s[28:29]
	global_load_dwordx4 v[28:31], v48, s[28:29] offset:512
	global_load_dwordx4 v[32:35], v48, s[28:29] offset:1024
	global_load_dwordx4 v[36:39], v49, s[28:29]
	global_load_dwordx4 v[40:43], v49, s[28:29] offset:512
	global_load_dwordx4 v[44:47], v49, s[28:29] offset:1024
	s_add_u32 s28, s28, 0x6000
	s_addc_u32 s29, s29, 0
	s_waitcnt vmcnt(6)
	ds_write_b128 v48, v[0:3] offset:0
	ds_write_b128 v48, v[4:7] offset:512
	ds_write_b128 v48, v[8:11] offset:1024
	ds_write_b128 v48, v[12:15] offset:12288
	ds_write_b128 v48, v[16:19] offset:12800
	ds_write_b128 v48, v[20:23] offset:13312
	global_load_dwordx4 v[0:3], v48, s[28:29]
	global_load_dwordx4 v[4:7], v48, s[28:29] offset:512
	global_load_dwordx4 v[8:11], v48, s[28:29] offset:1024
	global_load_dwordx4 v[12:15], v49, s[28:29]
	global_load_dwordx4 v[16:19], v49, s[28:29] offset:512
	global_load_dwordx4 v[20:23], v49, s[28:29] offset:1024
	s_add_u32 s28, s28, 0x6000
	s_addc_u32 s29, s29, 0
	s_waitcnt lgkmcnt(0)
	s_barrier
.Lb2_load_loop:
	s_cmp_eq_u32 s35, 0
	s_cbranch_scc1 .Lb2_ld_first
	ds_read_b128 v[68:71], v51 offset:16384
	ds_read_b128 v[72:75], v51 offset:16400
	ds_read_b128 v[76:79], v51 offset:16416
	ds_read_b128 v[80:83], v51 offset:16432
	s_waitcnt lgkmcnt(0)
	v_add_f32_e32 v68, v68, v69
	v_add_f32_e32 v70, v70, v71
	v_add_f32_e32 v72, v72, v73
	v_add_f32_e32 v74, v74, v75
	v_add_f32_e32 v76, v76, v77
	v_add_f32_e32 v78, v78, v79
	v_add_f32_e32 v80, v80, v81
	v_add_f32_e32 v82, v82, v83
	v_add_f32_e32 v68, v68, v70
	v_add_f32_e32 v72, v72, v74
	v_add_f32_e32 v76, v76, v78
	v_add_f32_e32 v80, v80, v82
	v_add_f32_e32 v68, v68, v72
	v_add_f32_e32 v76, v76, v80
	v_add_f32_e32 v68, v68, v76
	global_store_dword v60, v68, s[36:37]
	s_add_u32 s36, s36, 0x8000
	s_addc_u32 s37, s37, 0
.Lb2_ld_first:
	s_mov_b32 s35, 1
	s_waitcnt vmcnt(6)
	ds_write_b128 v48, v[24:27] offset:24576
	ds_write_b128 v48, v[28:31] offset:25088
	ds_write_b128 v48, v[32:35] offset:25600
	ds_write_b128 v48, v[36:39] offset:36864
	ds_write_b128 v48, v[40:43] offset:37376
	ds_write_b128 v48, v[44:47] offset:37888
	global_load_dwordx4 v[24:27], v48, s[28:29]
	global_load_dwordx4 v[28:31], v48, s[28:29] offset:512
	global_load_dwordx4 v[32:35], v48, s[28:29] offset:1024
	global_load_dwordx4 v[36:39], v49, s[28:29]
	global_load_dwordx4 v[40:43], v49, s[28:29] offset:512
	global_load_dwordx4 v[44:47], v49, s[28:29] offset:1024
	s_add_u32 s28, s28, 0x6000
	s_addc_u32 s29, s29, 0
	s_waitcnt lgkmcnt(0)
	s_barrier
	ds_read_b128 v[68:71], v51 offset:0
	ds_read_b128 v[72:75], v51 offset:16
	ds_read_b128 v[76:79], v51 offset:32
	ds_read_b128 v[80:83], v51 offset:48
	s_waitcnt lgkmcnt(0)
	v_add_f32_e32 v68, v68, v69
	v_add_f32_e32 v70, v70, v71
	v_add_f32_e32 v72, v72, v73
	v_add_f32_e32 v74, v74, v75
	v_add_f32_e32 v76, v76, v77
	v_add_f32_e32 v78, v78, v79
	v_add_f32_e32 v80, v80, v81
	v_add_f32_e32 v82, v82, v83
	v_add_f32_e32 v68, v68, v70
	v_add_f32_e32 v72, v72, v74
	v_add_f32_e32 v76, v76, v78
	v_add_f32_e32 v80, v80, v82
	v_add_f32_e32 v68, v68, v72
	v_add_f32_e32 v76, v76, v80
	v_add_f32_e32 v68, v68, v76
	global_store_dword v60, v68, s[36:37]
	s_add_u32 s36, s36, 0x8000
	s_addc_u32 s37, s37, 0
	s_waitcnt vmcnt(6)
	ds_write_b128 v48, v[0:3] offset:0
	ds_write_b128 v48, v[4:7] offset:512
	ds_write_b128 v48, v[8:11] offset:1024
	ds_write_b128 v48, v[12:15] offset:12288
	ds_write_b128 v48, v[16:19] offset:12800
	ds_write_b128 v48, v[20:23] offset:13312
	global_load_dwordx4 v[0:3], v48, s[28:29]
	global_load_dwordx4 v[4:7], v48, s[28:29] offset:512
	global_load_dwordx4 v[8:11], v48, s[28:29] offset:1024
	global_load_dwordx4 v[12:15], v49, s[28:29]
	global_load_dwordx4 v[16:19], v49, s[28:29] offset:512
	global_load_dwordx4 v[20:23], v49, s[28:29] offset:1024
	s_add_u32 s28, s28, 0x6000
	s_addc_u32 s29, s29, 0
	s_waitcnt lgkmcnt(0)
	s_barrier
	s_sub_u32 s34, s34, 1
	s_cmp_lg_u32 s34, 0
	s_cbranch_scc1 .Lb2_load_loop
	ds_read_b128 v[68:71], v51 offset:16384
	ds_read_b128 v[72:75], v51 offset:16400
	ds_read_b128 v[76:79], v51 offset:16416
	ds_read_b128 v[80:83], v51 offset:16432
	s_waitcnt lgkmcnt(0)
	v_add_f32_e32 v68, v68, v69
	v_add_f32_e32 v70, v70, v71
	v_add_f32_e32 v72, v72, v73
	v_add_f32_e32 v74, v74, v75
	v_add_f32_e32 v76, v76, v77
	v_add_f32_e32 v78, v78, v79
	v_add_f32_e32 v80, v80, v81
	v_add_f32_e32 v82, v82, v83
	v_add_f32_e32 v68, v68, v70
	v_add_f32_e32 v72, v72, v74
	v_add_f32_e32 v76, v76, v78
	v_add_f32_e32 v80, v80, v82
	v_add_f32_e32 v68, v68, v72
	v_add_f32_e32 v76, v76, v80
	v_add_f32_e32 v68, v68, v76
	global_store_dword v60, v68, s[36:37]
	s_add_u32 s36, s36, 0x8000
	s_addc_u32 s37, s37, 0
